# v64 + gating-mixer row-statistics loads marked non-temporal (read once, like the other mixer input streams)
# speedup vs baseline: 1.0036x; 1.0036x over previous
; #define lane (hw_lane())
; __device__ __forceinline__ void sgu_item(LAS unsigned char* wl, const bf16* proj, bf16* ymix, const float* vstat, const float* sgu_g, const bf16* Wm, const float* sgu_b, int chunk, int h, int lane) {
;     ...
;     for (int hh = 0; hh < 2; ++hh) { const f32x4* sp = (const f32x4*)(vstat + (R0 + lane + 64 * hh) * 16);
;         const f32x4 a = sp[0], b = sp[1], c = sp[2], d = sp[3];
;         const float s1 = ((a[0] + a[2]) + (b[0] + b[2])) + ((c[0] + c[2]) + (d[0] + d[2])), s2 = ((a[1] + a[3]) + (b[1] + b[3])) + ((c[1] + c[3]) + (d[1] + d[3]));
;         const float mean = s1 * (1.0f / 512.0f), var = fmaxf(s2 * (1.0f / 512.0f) - mean * mean, 0.f);
;         st[lane + 64 * hh] = (f32x2){mean, __builtin_amdgcn_rsqf(var + EPS)}; }
;     bf16x8 wmf[20];
;     { const bf16* wm = Wm + (size_t)(h * 128 + r) * 128 + q * 8; int f = 0;
; #pragma unroll
;       for (int ks = 0; ks < 4; ++ks)
; #pragma unroll
;         for (int tb = 2 * ks; tb < 8; ++tb) wmf[f++] = *(const bf16x8*)(wm + (size_t)(16 * tb) * 128 + ks * 32); }
;     float bias[8];
; #pragma unroll
;     for (int tb = 0; tb < 8; ++tb) bias[tb] = sgu_b[h * 128 + 16 * tb + r];
.LBB0_510:
	s_ashr_i32 s0, s5, 2
	s_ashr_i32 s1, s0, 31
	s_lshl_b64 s[8:9], s[0:1], 7
	v_mov_b32_e32 v1, s9
	v_or_b32_e32 v0, s8, v140
	v_lshlrev_b64 v[0:1], 6, v[0:1]
	v_lshl_add_u64 v[12:13], s[18:19], 0, v[0:1]
	global_load_dwordx4 v[0:3], v[12:13], off nt
	global_load_dwordx4 v[4:7], v[12:13], off offset:16 nt
	global_load_dwordx4 v[8:11], v[12:13], off offset:32 nt
	s_nop 0
	global_load_dwordx4 v[12:15], v[12:13], off offset:48 nt
	s_mov_b32 s10, 0x3b000000
	v_mov_b32_e32 v17, s9
	v_or_b32_e32 v16, s8, v142
	s_lshl_b32 s6, s5, 7
	s_and_b32 s6, s6, 0x180
	s_lshl_b64 s[8:9], s[0:1], 18
	s_mov_b64 s[20:21], 0
	v_lshlrev_b64 v[20:21], 6, v[16:17]
	v_or_b32_e32 v22, s6, v143
	v_lshl_add_u64 v[20:21], s[18:19], 0, v[20:21]
	v_lshlrev_b32_e32 v22, 2, v22
	global_load_dwordx4 v[24:27], v[20:21], off nt
	global_load_dwordx4 v[28:31], v[20:21], off offset:16 nt
	global_load_dwordx4 v[32:35], v[20:21], off offset:32 nt
	global_load_dwordx4 v[36:39], v[20:21], off offset:48 nt
	global_load_dword v162, v22, s[14:15]
	global_load_dword v164, v22, s[14:15] offset:64
	global_load_dword v166, v22, s[14:15] offset:128
	global_load_dword v168, v22, s[14:15] offset:192
	global_load_dword v170, v22, s[14:15] offset:256
	global_load_dword v172, v22, s[14:15] offset:320
	global_load_dword v174, v22, s[14:15] offset:384
	global_load_dword v176, v22, s[14:15] offset:448
	s_waitcnt vmcnt(12) lgkmcnt(0)
	v_pk_add_f32 v[0:1], v[0:1], v[2:3]
	v_pk_add_f32 v[2:3], v[4:5], v[6:7]
	v_pk_add_f32 v[4:5], v[8:9], v[10:11]
	v_pk_add_f32 v[6:7], v[12:13], v[14:15]
	v_pk_add_f32 v[0:1], v[0:1], v[2:3]
	v_pk_add_f32 v[2:3], v[4:5], v[6:7]
	s_nop 0
	v_pk_add_f32 v[0:1], v[0:1], v[2:3]
	v_lshlrev_b64 v[2:3], 6, v[16:17]
	v_pk_mul_f32 v[0:1], v[0:1], s[10:11] op_sel_hi:[1,0]
	v_lshl_add_u64 v[12:13], s[18:19], 0, v[2:3]
	v_fma_f32 v1, -v0, v0, v1
	v_max_f32_e32 v1, 0, v1
	v_add_f32_e32 v1, 0x358637bd, v1
	v_rsq_f32_e32 v1, v1
	v_or_b32_e32 v16, s6, v143
	v_lshlrev_b32_e32 v192, 8, v16
	v_lshlrev_b32_e32 v18, 2, v16
	ds_write_b64 v141, v[0:1] offset:10240
	v_lshl_add_u64 v[16:17], v[144:145], 0, v[192:193]
	s_movk_i32 s6, 0x1000
	v_add_co_u32_e32 v18, vcc, s6, v16
	s_movk_i32 s6, 0x2000
	s_nop 0
	v_addc_co_u32_e32 v19, vcc, 0, v17, vcc
	v_add_co_u32_e32 v20, vcc, s6, v16
	s_movk_i32 s6, 0x3000
	s_nop 0
	v_addc_co_u32_e32 v21, vcc, 0, v17, vcc
	v_add_co_u32_e32 v22, vcc, s6, v16
	s_movk_i32 s6, 0x4000
	s_nop 0
	v_addc_co_u32_e32 v23, vcc, 0, v17, vcc
	v_add_co_u32_e32 v52, vcc, s6, v16
	s_movk_i32 s6, 0x5000
	s_nop 0
	v_addc_co_u32_e32 v53, vcc, 0, v17, vcc
	v_add_co_u32_e32 v60, vcc, s6, v16
	s_movk_i32 s6, 0x6000
	s_nop 0
	v_addc_co_u32_e32 v61, vcc, 0, v17, vcc
	v_add_co_u32_e32 v68, vcc, s6, v16
	s_movk_i32 s6, 0x7000
	s_nop 0
	v_addc_co_u32_e32 v69, vcc, 0, v17, vcc
	v_add_co_u32_e32 v76, vcc, s6, v16
	s_lshl_b32 s6, s4, 1
	s_nop 0
	v_addc_co_u32_e32 v77, vcc, 0, v17, vcc
	s_waitcnt vmcnt(0)
	v_mov_b32_e32 v163, v162
	s_waitcnt lgkmcnt(0)
	v_pk_add_f32 v[0:1], v[24:25], v[26:27]
	v_pk_add_f32 v[2:3], v[28:29], v[30:31]
	v_pk_add_f32 v[4:5], v[32:33], v[34:35]
	v_pk_add_f32 v[6:7], v[36:37], v[38:39]
	v_pk_add_f32 v[0:1], v[0:1], v[2:3]
	v_pk_add_f32 v[2:3], v[4:5], v[6:7]
	v_mov_b32_e32 v165, v164
	v_pk_add_f32 v[0:1], v[0:1], v[2:3]
	v_mov_b32_e32 v167, v166
	v_pk_mul_f32 v[0:1], v[0:1], s[10:11] op_sel_hi:[1,0]
	s_and_b32 s10, s6, 0x300
	v_fma_f32 v1, -v0, v0, v1
	v_max_f32_e32 v1, 0, v1
	v_add_f32_e32 v1, 0x358637bd, v1
	v_rsq_f32_e32 v1, v1
	s_lshl_b32 s6, s4, 2
	s_and_b32 s86, s6, 0x600
	s_ashr_i32 s6, s5, 8
	ds_write_b64 v141, v[0:1] offset:10752
	global_load_dwordx4 v[0:3], v[16:17], off
	global_load_dwordx4 v[4:7], v[18:19], off
	global_load_dwordx4 v[8:11], v[20:21], off
	global_load_dwordx4 v[12:15], v[20:21], off offset:64
	s_nop 0
	global_load_dwordx4 v[16:19], v[22:23], off
	s_nop 0
	global_load_dwordx4 v[20:23], v[22:23], off offset:64
	s_nop 0
	global_load_dwordx4 v[24:27], v[52:53], off
	global_load_dwordx4 v[28:31], v[52:53], off offset:64
	global_load_dwordx4 v[32:35], v[68:69], off
	global_load_dwordx4 v[36:39], v[68:69], off offset:64
	global_load_dwordx4 v[40:43], v[76:77], off
	global_load_dwordx4 v[44:47], v[76:77], off offset:64
	global_load_dwordx4 v[48:51], v[60:61], off
	s_nop 0
	global_load_dwordx4 v[52:55], v[52:53], off offset:128
	s_nop 0
	global_load_dwordx4 v[56:59], v[60:61], off offset:64
	s_nop 0
	global_load_dwordx4 v[60:63], v[60:61], off offset:128
	s_nop 0
	global_load_dwordx4 v[64:67], v[68:69], off offset:128
	s_nop 0
	global_load_dwordx4 v[68:71], v[68:69], off offset:192
	s_nop 0
	global_load_dwordx4 v[72:75], v[76:77], off offset:128
	s_nop 0
	global_load_dwordx4 v[76:79], v[76:77], off offset:192
	s_mul_hi_i32 s11, s6, 0x1400000
	s_mul_i32 s12, s6, 0x1400000
	s_mul_hi_i32 s13, s6, 0x1c00000
	s_mul_i32 s6, s6, 0x1c00000
	s_add_u32 s1, s6, s8
	s_addc_u32 s9, s13, s9
	s_or_b32 s8, s1, s10
	s_mul_hi_i32 s1, s0, 0x60000
	s_mul_i32 s0, s0, 0x60000
	s_waitcnt lgkmcnt(0)
	s_add_u32 s0, s12, s0
	s_addc_u32 s1, s11, s1
	s_or_b32 s0, s0, s10
	v_lshl_add_u64 v[178:179], v[160:161], 0, s[86:87]
	v_mov_b32_e32 v169, v168
	v_mov_b32_e32 v171, v170
	v_mov_b32_e32 v173, v172
	v_mov_b32_e32 v175, v174
	v_mov_b32_e32 v177, v176
	v_lshl_add_u64 v[180:181], v[146:147], 0, s[8:9]
	v_lshl_add_u64 v[182:183], v[148:149], 0, s[8:9]
	v_lshl_add_u64 v[184:185], v[150:151], 0, s[8:9]
	v_lshl_add_u64 v[186:187], v[152:153], 0, s[0:1]
	v_lshl_add_u64 v[188:189], v[154:155], 0, s[0:1]
	v_lshl_add_u64 v[190:191], v[156:157], 0, s[0:1]
	v_lshl_add_u64 v[198:199], v[158:159], 0, s[0:1]
